# first K-loop trip peeled with SrcC=0 (no accumulator zeroing movs), on top of P0 RMSNorm rewrite + w_out transposes on heavy workgroups
# speedup vs baseline: 1.0381x; 1.0103x over previous
; #define PG8_STAGE(bufoff, gbase, voff) do { _Pragma("unroll") for (int _i = 0; _i < 2; ++_i) \
;         __builtin_amdgcn_global_load_lds((const unsigned*)((const char*)(gbase) + (voff)[_i]), (PG8_LAS unsigned*)(lds + (bufoff) + ldsw + _i * 8192), 16, 0, 0); } while (0)
; #define PG8_LDA(dst, b, h) do { _Pragma("unroll") for (int m = 0; m < 4; ++m) _Pragma("unroll") for (int k = 0; k < 2; ++k) dst[m][k] = *(const PG8_LAS bf16x8*)(lds + PG8_SA(b, h) + aoff + m * 2048 + k * 1024); } while (0)
; #define PG8_LDB(dst, b, h) do { _Pragma("unroll") for (int n = 0; n < 2; ++n) _Pragma("unroll") for (int k = 0; k < 2; ++k) dst[n][k] = *(const PG8_LAS bf16x8*)(lds + PG8_SB(b, h) + boff + n * 2048 + k * 1024); } while (0)
; #define PG8_WAIT_V(n) asm volatile("s_waitcnt vmcnt(" #n ")" ::: "memory")
; #define PG8_WAIT_L(n) asm volatile("s_waitcnt lgkmcnt(" #n ")" ::: "memory")
; #define PG8_BAR __builtin_amdgcn_s_barrier()
; #define PG8_SCHED __builtin_amdgcn_sched_barrier(0)
; template <class Epi, class Sched, bool ALIGN_EPI = false, bool SP2 = false>
; __device__ __forceinline__ void gemm_phase(PG8_LAS unsigned char* lds, const Gemm g, const Sched& S, const Epi& E) {
;     ...
;     for (int a = 0; a < 2; ++a)
; #pragma unroll
;         for (int b = 0; b < 2; ++b)
; #pragma unroll
;             for (int m = 0; m < 4; ++m)
; #pragma unroll
;                 for (int n = 0; n < 2; ++n) acc[a][b][m][n] = (f32x4){0.f, 0.f, 0.f, 0.f};
;     ...
;         const char* nA = has_next ? (const char*)g.A + (size_t)nxt.pm * tstep : cA; const char* nB = has_next ? (const char*)g.Bt + (size_t)nxt.pn * tstep : cB;
;         for (int t = 0; t < nt; t += 2) {
;             if constexpr (Epi::MID) { if (t == nt / 2) E.mid(acc, cur, wr, fr, lds); }
;             const bool last = (t == nt - 2);
;             const char* a1 = cA + (size_t)(t + 1) * kstep;
;             const char* a2 = last ? nA : cA + (size_t)(t + 2) * kstep; const char* b2 = last ? nB : cB + (size_t)(t + 2) * kstep;
;             const char* a3 = a2 + kstep; const char* b3 = b2 + kstep;
;             if (last && has_next) S.a_ready(nxt);
;             if constexpr (SP2) {
;             PG8_LDB(B0, 0, 0); PG8_LDB(B1, 0, 1); PG8_SCHED; PG8_LDA(At, 0, 0); PG8_STAGE(PG8_SA(1, 1), a1 + hstep, voffA);
;             PG8_WAIT_V(8); PG8_WAIT_L(0); PG8_BAR; PG8_MMA(0, 0, At, B0); PG8_MMA(0, 1, At, B1); PG8_BAR; PG8_SCHED;
.LBB0_132:
	s_ashr_i32 s87, s86, 31
	s_lshl_b64 s[0:1], s[86:87], 19
	s_add_u32 s88, s19, s0
	s_addc_u32 s89, s20, s1
	s_and_b64 s[0:1], s[12:13], exec
	s_cselect_b32 s36, s89, s17
	s_cselect_b32 s37, s88, s16
	s_ashr_i32 s85, s84, 31
	s_lshl_b64 s[0:1], s[84:85], 19
	s_add_u32 s90, s52, s0
	s_addc_u32 s91, s53, s1
	s_and_b64 s[0:1], s[12:13], exec
	s_cselect_b32 s38, s91, s3
	s_cselect_b32 s39, s90, s2
	s_add_u32 s0, s16, 0x40080
	s_addc_u32 s1, s17, 0
	s_add_u32 s40, s2, 0x100
	s_addc_u32 s41, s3, 0
	s_mov_b32 s42, -2
	ds_read_b128 v[82:85], v183
	ds_read_b128 v[134:137], v183 offset:1024
	ds_read_b128 v[138:141], v183 offset:2048
	ds_read_b128 v[188:191], v183 offset:3072
	ds_read_b128 v[192:195], v184
	ds_read_b128 v[196:199], v184 offset:1024
	ds_read_b128 v[200:203], v184 offset:2048
	ds_read_b128 v[204:207], v184 offset:3072
	s_add_u32 s2, s0, 0xfffc0080
	s_addc_u32 s3, s1, -1
	s_cmp_eq_u32 s42, 12
	s_cselect_b32 s17, s36, s3
	s_cselect_b32 s16, s37, s2
	s_cselect_b32 s3, s38, s41
	s_cselect_b32 s2, s39, s40
	v_lshl_add_u64 v[228:229], s[0:1], 0, v[152:153]
	s_add_i32 m0, s21, 0xc000
	ds_read_b128 v[208:211], v185
	ds_read_b128 v[212:215], v185 offset:1024
	ds_read_b128 v[216:219], v185 offset:2048
	ds_read_b128 v[220:223], v185 offset:3072
	ds_read_b128 v[224:227], v185 offset:4096
	ds_read_b128 v[232:235], v185 offset:5120
	ds_read_b128 v[236:239], v185 offset:6144
	ds_read_b128 v[240:243], v185 offset:7168
	global_load_lds_dwordx4 v[228:229], off
	v_lshl_add_u64 v[228:229], s[0:1], 0, v[154:155]
	s_add_i32 m0, s21, 0xe000
	s_nop 0
	global_load_lds_dwordx4 v[228:229], off
	s_waitcnt vmcnt(8)
	s_waitcnt lgkmcnt(0)
	s_barrier
	s_setprio 1
	s_waitcnt lgkmcnt(0)
	v_mfma_f32_16x16x32_bf16 v[122:125], v[82:85], v[208:211], 0
	v_mfma_f32_16x16x32_bf16 v[130:133], v[138:141], v[208:211], 0
	v_mfma_f32_16x16x32_bf16 v[106:109], v[82:85], v[216:219], 0
	v_mfma_f32_16x16x32_bf16 v[118:121], v[138:141], v[216:219], 0
	v_mfma_f32_16x16x32_bf16 v[90:93], v[82:85], v[224:227], 0
	v_mfma_f32_16x16x32_bf16 v[102:105], v[138:141], v[224:227], 0
	v_mfma_f32_16x16x32_bf16 v[68:71], v[82:85], v[236:239], 0
	v_mfma_f32_16x16x32_bf16 v[76:79], v[138:141], v[236:239], 0
	v_mfma_f32_16x16x32_bf16 v[122:125], v[134:137], v[212:215], v[122:125]
	v_mfma_f32_16x16x32_bf16 v[130:133], v[188:191], v[212:215], v[130:133]
	v_mfma_f32_16x16x32_bf16 v[106:109], v[134:137], v[220:223], v[106:109]
	v_mfma_f32_16x16x32_bf16 v[118:121], v[188:191], v[220:223], v[118:121]
	v_mfma_f32_16x16x32_bf16 v[90:93], v[134:137], v[232:235], v[90:93]
	v_mfma_f32_16x16x32_bf16 v[102:105], v[188:191], v[232:235], v[102:105]
	v_mfma_f32_16x16x32_bf16 v[68:71], v[134:137], v[240:243], v[68:71]
	v_mfma_f32_16x16x32_bf16 v[76:79], v[188:191], v[240:243], v[76:79]
	s_setprio 0
	s_setprio 1
	v_mfma_f32_16x16x32_bf16 v[126:129], v[192:195], v[208:211], 0
	v_mfma_f32_16x16x32_bf16 v[114:117], v[200:203], v[208:211], 0
	v_mfma_f32_16x16x32_bf16 v[110:113], v[192:195], v[216:219], 0
	v_mfma_f32_16x16x32_bf16 v[94:97], v[200:203], v[216:219], 0
	v_mfma_f32_16x16x32_bf16 v[98:101], v[192:195], v[224:227], 0
	v_mfma_f32_16x16x32_bf16 v[86:89], v[200:203], v[224:227], 0
	v_mfma_f32_16x16x32_bf16 v[72:75], v[192:195], v[236:239], 0
	v_mfma_f32_16x16x32_bf16 v[48:51], v[200:203], v[236:239], 0
	v_mfma_f32_16x16x32_bf16 v[126:129], v[196:199], v[212:215], v[126:129]
	v_mfma_f32_16x16x32_bf16 v[114:117], v[204:207], v[212:215], v[114:117]
	v_mfma_f32_16x16x32_bf16 v[110:113], v[196:199], v[220:223], v[110:113]
	v_mfma_f32_16x16x32_bf16 v[94:97], v[204:207], v[220:223], v[94:97]
	v_mfma_f32_16x16x32_bf16 v[98:101], v[196:199], v[232:235], v[98:101]
	v_mfma_f32_16x16x32_bf16 v[86:89], v[204:207], v[232:235], v[86:89]
	v_mfma_f32_16x16x32_bf16 v[72:75], v[196:199], v[240:243], v[72:75]
	v_mfma_f32_16x16x32_bf16 v[48:51], v[204:207], v[240:243], v[48:51]
	s_setprio 0
	s_barrier
	s_add_i32 s33, s30, s18
	v_lshl_add_u64 v[228:229], s[2:3], 0, v[142:143]
	s_mov_b32 m0, s33
	ds_read_b128 v[208:211], v185 offset:16384
	ds_read_b128 v[212:215], v185 offset:17408
	ds_read_b128 v[216:219], v185 offset:18432
	ds_read_b128 v[220:223], v185 offset:19456
	ds_read_b128 v[224:227], v185 offset:20480
	ds_read_b128 v[232:235], v185 offset:21504
	ds_read_b128 v[236:239], v185 offset:22528
	ds_read_b128 v[240:243], v185 offset:23552
	global_load_lds_dwordx4 v[228:229], off
	s_add_i32 m0, s33, 0x2000
	s_add_u32 s44, s2, 0x40000
	v_lshl_add_u64 v[244:245], s[2:3], 0, v[144:145]
	s_addc_u32 s45, s3, 0
	s_add_i32 s33, s31, s18
	global_load_lds_dwordx4 v[244:245], off
	v_lshl_add_u64 v[246:247], s[44:45], 0, v[142:143]
	s_mov_b32 m0, s33
	v_lshl_add_u64 v[248:249], s[16:17], 0, v[144:145]
	global_load_lds_dwordx4 v[246:247], off
	v_lshl_add_u64 v[246:247], s[44:45], 0, v[144:145]
	s_add_i32 m0, s33, 0x2000
	s_nop 0
	global_load_lds_dwordx4 v[246:247], off
	v_lshl_add_u64 v[246:247], s[16:17], 0, v[142:143]
	s_mov_b32 m0, s21
	s_nop 0
	global_load_lds_dwordx4 v[246:247], off
	s_mov_b32 m0, s22
	s_nop 0
	global_load_lds_dwordx4 v[248:249], off
	s_waitcnt vmcnt(8)
	s_waitcnt lgkmcnt(0)
	s_barrier
; #define PG8_STAGE(bufoff, gbase, voff) do { _Pragma("unroll") for (int _i = 0; _i < 2; ++_i) \
;         __builtin_amdgcn_global_load_lds((const unsigned*)((const char*)(gbase) + (voff)[_i]), (PG8_LAS unsigned*)(lds + (bufoff) + ldsw + _i * 8192), 16, 0, 0); } while (0)
; #define PG8_LDA(dst, b, h) do { _Pragma("unroll") for (int m = 0; m < 4; ++m) _Pragma("unroll") for (int k = 0; k < 2; ++k) dst[m][k] = *(const PG8_LAS bf16x8*)(lds + PG8_SA(b, h) + aoff + m * 2048 + k * 1024); } while (0)
; #define PG8_LDB(dst, b, h) do { _Pragma("unroll") for (int n = 0; n < 2; ++n) _Pragma("unroll") for (int k = 0; k < 2; ++k) dst[n][k] = *(const PG8_LAS bf16x8*)(lds + PG8_SB(b, h) + boff + n * 2048 + k * 1024); } while (0)
; #define PG8_MMA(ai, bj, At, Bt) do { __builtin_amdgcn_s_setprio(1); _Pragma("unroll") for (int m = 0; m < 4; ++m) _Pragma("unroll") for (int n = 0; n < 2; ++n) _Pragma("unroll") for (int k = 0; k < 2; ++k) \
;         acc[ai][bj][m][n] = __builtin_amdgcn_mfma_f32_16x16x32_bf16(Bt[n][k], At[m][k], acc[ai][bj][m][n], 0, 0, 0); __builtin_amdgcn_s_setprio(0); } while (0)
; #define PG8_WAIT_V(n) asm volatile("s_waitcnt vmcnt(" #n ")" ::: "memory")
; #define PG8_WAIT_L(n) asm volatile("s_waitcnt lgkmcnt(" #n ")" ::: "memory")
; #define PG8_BAR __builtin_amdgcn_s_barrier()
; #define PG8_SCHED __builtin_amdgcn_sched_barrier(0)
; template <class Epi, class Sched, bool ALIGN_EPI = false, bool SP2 = false>
; __device__ __forceinline__ void gemm_phase(PG8_LAS unsigned char* lds, const Gemm g, const Sched& S, const Epi& E) {
;     ...
;             PG8_LDA(At, 0, 1); PG8_STAGE(PG8_SB(0, 0), b2, voffB); PG8_STAGE(PG8_SB(0, 1), b2 + hstep, voffB); PG8_STAGE(PG8_SA(0, 0), a2, voffA);
;             PG8_WAIT_V(8); PG8_WAIT_L(0); PG8_BAR; PG8_MMA(1, 0, At, B0); PG8_MMA(1, 1, At, B1); PG8_BAR; PG8_SCHED;
;             PG8_LDB(B0, 1, 0); PG8_LDB(B1, 1, 1); PG8_SCHED; PG8_LDA(At, 1, 0); PG8_STAGE(PG8_SA(0, 1), a2 + hstep, voffA);
;             PG8_WAIT_V(8); PG8_WAIT_L(0); PG8_BAR; PG8_MMA(0, 0, At, B0); PG8_MMA(0, 1, At, B1); PG8_BAR; PG8_SCHED;
	s_setprio 1
	s_waitcnt lgkmcnt(0)
	v_mfma_f32_16x16x32_bf16 v[44:47], v[82:85], v[208:211], 0
	v_mfma_f32_16x16x32_bf16 v[60:63], v[138:141], v[208:211], 0
	v_mfma_f32_16x16x32_bf16 v[28:31], v[82:85], v[216:219], 0
	v_mfma_f32_16x16x32_bf16 v[40:43], v[138:141], v[216:219], 0
	v_mfma_f32_16x16x32_bf16 v[12:15], v[82:85], v[224:227], 0
	v_mfma_f32_16x16x32_bf16 v[24:27], v[138:141], v[224:227], 0
	v_mfma_f32_16x16x32_bf16 v[4:7], v[82:85], v[236:239], 0
	v_mfma_f32_16x16x32_bf16 v[64:67], v[138:141], v[236:239], 0
	v_mfma_f32_16x16x32_bf16 v[44:47], v[134:137], v[212:215], v[44:47]
	v_mfma_f32_16x16x32_bf16 v[60:63], v[188:191], v[212:215], v[60:63]
	v_mfma_f32_16x16x32_bf16 v[28:31], v[134:137], v[220:223], v[28:31]
	v_mfma_f32_16x16x32_bf16 v[40:43], v[188:191], v[220:223], v[40:43]
	v_mfma_f32_16x16x32_bf16 v[12:15], v[134:137], v[232:235], v[12:15]
	v_mfma_f32_16x16x32_bf16 v[24:27], v[188:191], v[232:235], v[24:27]
	v_mfma_f32_16x16x32_bf16 v[4:7], v[134:137], v[240:243], v[4:7]
	v_mfma_f32_16x16x32_bf16 v[64:67], v[188:191], v[240:243], v[64:67]
	s_setprio 0
	s_setprio 1
	v_mfma_f32_16x16x32_bf16 v[56:59], v[192:195], v[208:211], 0
	v_mfma_f32_16x16x32_bf16 v[32:35], v[200:203], v[208:211], 0
	v_mfma_f32_16x16x32_bf16 v[36:39], v[192:195], v[216:219], 0
	v_mfma_f32_16x16x32_bf16 v[16:19], v[200:203], v[216:219], 0
	v_mfma_f32_16x16x32_bf16 v[20:23], v[192:195], v[224:227], 0
	v_mfma_f32_16x16x32_bf16 v[8:11], v[200:203], v[224:227], 0
	v_mfma_f32_16x16x32_bf16 v[52:55], v[192:195], v[236:239], 0
	v_mfma_f32_16x16x32_bf16 v[0:3], v[200:203], v[236:239], 0
	v_mfma_f32_16x16x32_bf16 v[56:59], v[196:199], v[212:215], v[56:59]
	v_mfma_f32_16x16x32_bf16 v[32:35], v[204:207], v[212:215], v[32:35]
	v_mfma_f32_16x16x32_bf16 v[36:39], v[196:199], v[220:223], v[36:39]
	v_mfma_f32_16x16x32_bf16 v[16:19], v[204:207], v[220:223], v[16:19]
	v_mfma_f32_16x16x32_bf16 v[20:23], v[196:199], v[232:235], v[20:23]
	v_mfma_f32_16x16x32_bf16 v[8:11], v[204:207], v[232:235], v[8:11]
	v_mfma_f32_16x16x32_bf16 v[52:55], v[196:199], v[240:243], v[52:55]
	v_mfma_f32_16x16x32_bf16 v[0:3], v[204:207], v[240:243], v[0:3]
	s_setprio 0
	s_barrier
	s_add_i32 s33, 0, 0x18000
	v_add_u32_e32 v146, s33, v173
	s_add_i32 s43, 0, 0x1c000
	ds_read_b128 v[82:85], v146
	ds_read_b128 v[134:137], v146 offset:1024
	ds_read_b128 v[138:141], v146 offset:2048
	ds_read_b128 v[188:191], v146 offset:3072
	v_add_u32_e32 v146, s43, v173
	ds_read_b128 v[192:195], v146
	ds_read_b128 v[196:199], v146 offset:1024
	ds_read_b128 v[200:203], v146 offset:2048
	ds_read_b128 v[204:207], v146 offset:3072
	s_add_u32 s16, s16, 0x40000
	s_addc_u32 s17, s17, 0
	s_mov_b32 m0, s23
	v_lshl_add_u64 v[250:251], s[16:17], 0, v[142:143]
	ds_read_b128 v[208:211], v185 offset:32768
	ds_read_b128 v[212:215], v185 offset:33792
	ds_read_b128 v[216:219], v185 offset:34816
	ds_read_b128 v[220:223], v185 offset:35840
	ds_read_b128 v[224:227], v185 offset:36864
	ds_read_b128 v[232:235], v185 offset:37888
	ds_read_b128 v[236:239], v185 offset:38912
	ds_read_b128 v[240:243], v185 offset:39936
	global_load_lds_dwordx4 v[250:251], off
	v_lshl_add_u64 v[250:251], s[16:17], 0, v[144:145]
	s_mov_b32 m0, s24
	s_nop 0
	global_load_lds_dwordx4 v[250:251], off
	s_waitcnt vmcnt(8)
	s_waitcnt lgkmcnt(0)
	s_barrier
	s_setprio 1
	s_waitcnt lgkmcnt(0)
	v_mfma_f32_16x16x32_bf16 v[122:125], v[82:85], v[208:211], v[122:125]
	v_mfma_f32_16x16x32_bf16 v[130:133], v[138:141], v[208:211], v[130:133]
	v_mfma_f32_16x16x32_bf16 v[106:109], v[82:85], v[216:219], v[106:109]
	v_mfma_f32_16x16x32_bf16 v[118:121], v[138:141], v[216:219], v[118:121]
	v_mfma_f32_16x16x32_bf16 v[90:93], v[82:85], v[224:227], v[90:93]
	v_mfma_f32_16x16x32_bf16 v[102:105], v[138:141], v[224:227], v[102:105]
	v_mfma_f32_16x16x32_bf16 v[68:71], v[82:85], v[236:239], v[68:71]
	v_mfma_f32_16x16x32_bf16 v[76:79], v[138:141], v[236:239], v[76:79]
	v_mfma_f32_16x16x32_bf16 v[122:125], v[134:137], v[212:215], v[122:125]
	v_mfma_f32_16x16x32_bf16 v[130:133], v[188:191], v[212:215], v[130:133]
	v_mfma_f32_16x16x32_bf16 v[106:109], v[134:137], v[220:223], v[106:109]
	v_mfma_f32_16x16x32_bf16 v[118:121], v[188:191], v[220:223], v[118:121]
	v_mfma_f32_16x16x32_bf16 v[90:93], v[134:137], v[232:235], v[90:93]
	v_mfma_f32_16x16x32_bf16 v[102:105], v[188:191], v[232:235], v[102:105]
	v_mfma_f32_16x16x32_bf16 v[68:71], v[134:137], v[240:243], v[68:71]
	v_mfma_f32_16x16x32_bf16 v[76:79], v[188:191], v[240:243], v[76:79]
	s_setprio 0
	s_setprio 1
	v_mfma_f32_16x16x32_bf16 v[126:129], v[192:195], v[208:211], v[126:129]
	v_mfma_f32_16x16x32_bf16 v[114:117], v[200:203], v[208:211], v[114:117]
	v_mfma_f32_16x16x32_bf16 v[110:113], v[192:195], v[216:219], v[110:113]
	v_mfma_f32_16x16x32_bf16 v[94:97], v[200:203], v[216:219], v[94:97]
	v_mfma_f32_16x16x32_bf16 v[98:101], v[192:195], v[224:227], v[98:101]
	v_mfma_f32_16x16x32_bf16 v[86:89], v[200:203], v[224:227], v[86:89]
	v_mfma_f32_16x16x32_bf16 v[72:75], v[192:195], v[236:239], v[72:75]
	v_mfma_f32_16x16x32_bf16 v[48:51], v[200:203], v[236:239], v[48:51]
	v_mfma_f32_16x16x32_bf16 v[126:129], v[196:199], v[212:215], v[126:129]
	v_mfma_f32_16x16x32_bf16 v[114:117], v[204:207], v[212:215], v[114:117]
	v_mfma_f32_16x16x32_bf16 v[110:113], v[196:199], v[220:223], v[110:113]
	v_mfma_f32_16x16x32_bf16 v[94:97], v[204:207], v[220:223], v[94:97]
	v_mfma_f32_16x16x32_bf16 v[98:101], v[196:199], v[232:235], v[98:101]
	v_mfma_f32_16x16x32_bf16 v[86:89], v[204:207], v[232:235], v[86:89]
	v_mfma_f32_16x16x32_bf16 v[72:75], v[196:199], v[240:243], v[72:75]
	v_mfma_f32_16x16x32_bf16 v[48:51], v[204:207], v[240:243], v[48:51]
	s_setprio 0
	s_barrier
; #define PG8_STAGE(bufoff, gbase, voff) do { _Pragma("unroll") for (int _i = 0; _i < 2; ++_i) \
;         __builtin_amdgcn_global_load_lds((const unsigned*)((const char*)(gbase) + (voff)[_i]), (PG8_LAS unsigned*)(lds + (bufoff) + ldsw + _i * 8192), 16, 0, 0); } while (0)
; #define PG8_LDA(dst, b, h) do { _Pragma("unroll") for (int m = 0; m < 4; ++m) _Pragma("unroll") for (int k = 0; k < 2; ++k) dst[m][k] = *(const PG8_LAS bf16x8*)(lds + PG8_SA(b, h) + aoff + m * 2048 + k * 1024); } while (0)
; #define PG8_MMA(ai, bj, At, Bt) do { __builtin_amdgcn_s_setprio(1); _Pragma("unroll") for (int m = 0; m < 4; ++m) _Pragma("unroll") for (int n = 0; n < 2; ++n) _Pragma("unroll") for (int k = 0; k < 2; ++k) \
;         acc[ai][bj][m][n] = __builtin_amdgcn_mfma_f32_16x16x32_bf16(Bt[n][k], At[m][k], acc[ai][bj][m][n], 0, 0, 0); __builtin_amdgcn_s_setprio(0); } while (0)
; #define PG8_WAIT_V(n) asm volatile("s_waitcnt vmcnt(" #n ")" ::: "memory")
; #define PG8_WAIT_L(n) asm volatile("s_waitcnt lgkmcnt(" #n ")" ::: "memory")
; #define PG8_BAR __builtin_amdgcn_s_barrier()
; #define PG8_SCHED __builtin_amdgcn_sched_barrier(0)
; template <class Epi, class Sched, bool ALIGN_EPI = false, bool SP2 = false>
; __device__ __forceinline__ void gemm_phase(PG8_LAS unsigned char* lds, const Gemm g, const Sched& S, const Epi& E) {
;     ...
;         for (int t = 0; t < nt; t += 2) {
;     ...
;             PG8_WAIT_V(8); PG8_WAIT_L(0); PG8_BAR; PG8_MMA(0, 0, At, B0); PG8_MMA(0, 1, At, B1); PG8_BAR; PG8_SCHED;
;             PG8_LDA(At, 1, 1); PG8_STAGE(PG8_SB(1, 0), b3, voffB); PG8_STAGE(PG8_SB(1, 1), b3 + hstep, voffB); PG8_STAGE(PG8_SA(1, 0), a3, voffA);
;             PG8_WAIT_V(8); PG8_WAIT_L(0); PG8_BAR; PG8_MMA(1, 0, At, B0); PG8_MMA(1, 1, At, B1); PG8_BAR; PG8_SCHED;
	s_add_i32 s16, s33, s18
	v_lshl_add_u64 v[228:229], v[228:229], 0, s[66:67]
	s_mov_b32 m0, s16
	ds_read_b128 v[208:211], v185 offset:49152
	ds_read_b128 v[212:215], v185 offset:50176
	ds_read_b128 v[216:219], v185 offset:51200
	ds_read_b128 v[220:223], v185 offset:52224
	ds_read_b128 v[224:227], v185 offset:53248
	ds_read_b128 v[232:235], v185 offset:54272
	ds_read_b128 v[236:239], v185 offset:55296
	ds_read_b128 v[240:243], v185 offset:56320
	global_load_lds_dwordx4 v[228:229], off
	s_add_i32 m0, s16, 0x2000
	s_add_u32 s2, s2, 0x40080
	v_lshl_add_u64 v[228:229], v[244:245], 0, s[66:67]
	s_addc_u32 s3, s3, 0
	s_add_i32 s16, s43, s18
	global_load_lds_dwordx4 v[228:229], off
	v_lshl_add_u64 v[228:229], s[2:3], 0, v[142:143]
	s_mov_b32 m0, s16
	s_nop 0
	global_load_lds_dwordx4 v[228:229], off
	v_lshl_add_u64 v[228:229], s[2:3], 0, v[144:145]
	s_add_i32 m0, s16, 0x2000
	s_nop 0
	global_load_lds_dwordx4 v[228:229], off
	v_lshl_add_u64 v[228:229], v[246:247], 0, s[66:67]
	s_mov_b32 m0, s27
	s_nop 0
	global_load_lds_dwordx4 v[228:229], off
	v_lshl_add_u64 v[228:229], v[248:249], 0, s[66:67]
	s_mov_b32 m0, s28
	s_nop 0
	global_load_lds_dwordx4 v[228:229], off
	s_waitcnt vmcnt(8)
	s_waitcnt lgkmcnt(0)
	s_barrier
	s_setprio 1
	s_waitcnt lgkmcnt(0)
	v_mfma_f32_16x16x32_bf16 v[44:47], v[82:85], v[208:211], v[44:47]
	v_mfma_f32_16x16x32_bf16 v[60:63], v[138:141], v[208:211], v[60:63]
	v_mfma_f32_16x16x32_bf16 v[28:31], v[82:85], v[216:219], v[28:31]
	v_mfma_f32_16x16x32_bf16 v[40:43], v[138:141], v[216:219], v[40:43]
	v_mfma_f32_16x16x32_bf16 v[12:15], v[82:85], v[224:227], v[12:15]
	v_mfma_f32_16x16x32_bf16 v[24:27], v[138:141], v[224:227], v[24:27]
	v_mfma_f32_16x16x32_bf16 v[4:7], v[82:85], v[236:239], v[4:7]
	v_mfma_f32_16x16x32_bf16 v[64:67], v[138:141], v[236:239], v[64:67]
	v_mfma_f32_16x16x32_bf16 v[44:47], v[134:137], v[212:215], v[44:47]
	v_mfma_f32_16x16x32_bf16 v[60:63], v[188:191], v[212:215], v[60:63]
	v_mfma_f32_16x16x32_bf16 v[28:31], v[134:137], v[220:223], v[28:31]
	v_mfma_f32_16x16x32_bf16 v[40:43], v[188:191], v[220:223], v[40:43]
	v_mfma_f32_16x16x32_bf16 v[12:15], v[134:137], v[232:235], v[12:15]
	v_mfma_f32_16x16x32_bf16 v[24:27], v[188:191], v[232:235], v[24:27]
	v_mfma_f32_16x16x32_bf16 v[4:7], v[134:137], v[240:243], v[4:7]
	v_mfma_f32_16x16x32_bf16 v[64:67], v[188:191], v[240:243], v[64:67]
	s_setprio 0
	s_setprio 1
	v_mfma_f32_16x16x32_bf16 v[56:59], v[192:195], v[208:211], v[56:59]
	v_mfma_f32_16x16x32_bf16 v[32:35], v[200:203], v[208:211], v[32:35]
	v_mfma_f32_16x16x32_bf16 v[36:39], v[192:195], v[216:219], v[36:39]
	v_mfma_f32_16x16x32_bf16 v[16:19], v[200:203], v[216:219], v[16:19]
	v_mfma_f32_16x16x32_bf16 v[20:23], v[192:195], v[224:227], v[20:23]
	v_mfma_f32_16x16x32_bf16 v[8:11], v[200:203], v[224:227], v[8:11]
	v_mfma_f32_16x16x32_bf16 v[52:55], v[192:195], v[236:239], v[52:55]
	v_mfma_f32_16x16x32_bf16 v[0:3], v[200:203], v[236:239], v[0:3]
	v_mfma_f32_16x16x32_bf16 v[56:59], v[196:199], v[212:215], v[56:59]
	v_mfma_f32_16x16x32_bf16 v[32:35], v[204:207], v[212:215], v[32:35]
	v_mfma_f32_16x16x32_bf16 v[36:39], v[196:199], v[220:223], v[36:39]
	v_mfma_f32_16x16x32_bf16 v[16:19], v[204:207], v[220:223], v[16:19]
	v_mfma_f32_16x16x32_bf16 v[20:23], v[196:199], v[232:235], v[20:23]
	v_mfma_f32_16x16x32_bf16 v[8:11], v[204:207], v[232:235], v[8:11]
	v_mfma_f32_16x16x32_bf16 v[52:55], v[196:199], v[240:243], v[52:55]
	v_mfma_f32_16x16x32_bf16 v[0:3], v[204:207], v[240:243], v[0:3]
	s_setprio 0
	s_barrier
	s_add_i32 s42, s42, 2
	s_add_u32 s0, s0, 0x100
	s_addc_u32 s1, s1, 0
	s_add_u32 s40, s40, 0x100
	s_addc_u32 s41, s41, 0
